# attention: max3 chains + dedicated dj>=3 tile path (direct accumulator init, no select/move chains)
# speedup vs baseline: 1.0085x; 1.0078x over previous
; #define LAS __attribute__((address_space(3)))
; #define MFMA32(a, b, c) __builtin_amdgcn_mfma_f32_32x32x16_bf16((a), (b), (c), 0, 0, 0)
; __device__ __forceinline__ int crow(int r, int hi) { return (r & 3) + 8 * (r >> 2) + 4 * hi; }
; __device__ __forceinline__ void qk_tile(f32x16& s0, f32x16& s1, const LAS unsigned char* Kt, const bf16x8 (&qf)[4], int r32, int hi) {
; #pragma unroll
;     for (int d0 = 0; d0 < 4; ++d0) {
;         const bf16x8 k0 = *(const LAS bf16x8*)(Kt + r32 * TPITCH + (16 * d0 + 8 * hi) * 2);
;         const bf16x8 k1 = *(const LAS bf16x8*)(Kt + (r32 + 32) * TPITCH + (16 * d0 + 8 * hi) * 2);
;         s0 = MFMA32(k0, qf[d0], s0); s1 = MFMA32(k1, qf[d0], s1);
;     }
; }
; template <int MODE> ...
;     ...
;         f32x16 s0, s1; const int dj = qb - j;
;         const bool sel = (MODE == 0) ? (((selmask >> j) & 1u) != 0u) : true;
;         if (dj >= 3) {
;             const float bi = sel ? b31 : -INFINITY;
; #pragma unroll
;             for (int r = 0; r < 16; ++r) { s0[r] = bi; s1[r] = bi; }
;         } else {
;             const int e0 = 64 * dj + iq + 64;
; #pragma unroll
;             for (int r = 0; r < 16; ++r) { const int kl = crow(r, hi); s0[r] = biasW[e0 - kl]; s1[r] = biasW[e0 - kl - 32]; }
;         }
;         qk_tile(s0, s1, Kt, qf, r32, hi);
.LBB0_846:
	s_andn2_b64 vcc, exec, s[12:13]
	s_cbranch_vccnz .LBB0_848
	s_waitcnt lgkmcnt(0)
	v_cndmask_b32_e64 v84, v234, v168, s[4:5]
	s_and_b32 s12, s14, 1
	s_mul_i32 s13, s12, 0x4800
	v_lshlrev_b32_e32 v124, 4, v171
	v_mov_b32_e32 v85, v84
	v_add3_u32 v125, s13, v237, v124
	ds_read_b128 v[112:115], v125
	ds_read_b128 v[116:119], v125 offset:4608
	ds_read_b128 v[120:123], v125 offset:32
	ds_read_b128 v[126:129], v125 offset:4640
	v_mov_b64_e32 v[68:69], v[84:85]
	v_mov_b64_e32 v[70:71], v[84:85]
	v_mov_b64_e32 v[72:73], v[84:85]
	v_mov_b64_e32 v[74:75], v[84:85]
	v_mov_b64_e32 v[76:77], v[84:85]
	v_mov_b64_e32 v[78:79], v[84:85]
	v_mov_b64_e32 v[80:81], v[84:85]
	v_mov_b64_e32 v[82:83], v[84:85]
	v_mov_b64_e32 v[86:87], v[84:85]
	v_mov_b64_e32 v[88:89], v[84:85]
	v_mov_b64_e32 v[90:91], v[84:85]
	v_mov_b64_e32 v[92:93], v[84:85]
	v_mov_b64_e32 v[94:95], v[84:85]
	v_mov_b64_e32 v[96:97], v[84:85]
	v_mov_b64_e32 v[98:99], v[84:85]
	s_waitcnt lgkmcnt(3)
	v_mfma_f32_32x32x16_bf16 v[68:83], v[112:115], v[142:145], v[68:83]
	ds_read_b128 v[112:115], v125 offset:64
	s_waitcnt lgkmcnt(3)
	v_mfma_f32_32x32x16_bf16 v[84:99], v[116:119], v[142:145], v[84:99]
	ds_read_b128 v[116:119], v125 offset:4672
	s_waitcnt lgkmcnt(3)
	v_mfma_f32_32x32x16_bf16 v[68:83], v[120:123], v[134:137], v[68:83]
	ds_read_b128 v[120:123], v125 offset:96
	s_waitcnt lgkmcnt(3)
	v_mfma_f32_32x32x16_bf16 v[84:99], v[126:129], v[134:137], v[84:99]
	ds_read_b128 v[126:129], v125 offset:4704
	s_waitcnt lgkmcnt(3)
	v_mfma_f32_32x32x16_bf16 v[68:83], v[112:115], v[138:141], v[68:83]
	s_waitcnt lgkmcnt(2)
	v_mfma_f32_32x32x16_bf16 v[84:99], v[116:119], v[138:141], v[84:99]
	s_waitcnt lgkmcnt(1)
	v_mfma_f32_32x32x16_bf16 v[68:83], v[120:123], v[146:149], v[68:83]
	s_waitcnt lgkmcnt(0)
	v_mfma_f32_32x32x16_bf16 v[84:99], v[126:129], v[146:149], v[84:99]
	s_nop 11
	v_mov_b64_e32 v[114:115], v[92:93]
	v_mov_b64_e32 v[116:117], v[88:89]
	v_mov_b64_e32 v[118:119], v[84:85]
	v_mov_b64_e32 v[112:113], v[82:83]
	v_mov_b64_e32 v[92:93], v[80:81]
	v_mov_b64_e32 v[88:89], v[78:79]
	v_mov_b64_e32 v[84:85], v[76:77]
	v_mov_b64_e32 v[80:81], v[74:75]
	v_mov_b64_e32 v[76:77], v[72:73]
	v_mov_b64_e32 v[72:73], v[70:71]
	s_branch .LBB0_850

; #define LAS __attribute__((address_space(3)))
; #define MFMA32(a, b, c) __builtin_amdgcn_mfma_f32_32x32x16_bf16((a), (b), (c), 0, 0, 0)
; __device__ __forceinline__ void pv_tile(f32x16 (&o)[2], const LAS unsigned char* Vt, const f32x16& p0, const f32x16& p1, int r32, int hi) {
; #pragma unroll
;     for (int j = 0; j < 2; ++j) { const bf16x8 pw = pack8(p0, j);
; #pragma unroll
;         for (int db = 0; db < 2; ++db) { const bf16x8 vf = *(const LAS bf16x8*)(Vt + (r32 + 32 * db) * TPITCH + (16 * j + 8 * hi) * 2); o[db] = MFMA32(vf, pw, o[db]); } }
; #pragma unroll
;     for (int j = 0; j < 2; ++j) { const bf16x8 pw = pack8(p1, j);
; #pragma unroll
;         for (int db = 0; db < 2; ++db) { const bf16x8 vf = *(const LAS bf16x8*)(Vt + (r32 + 32 * db) * TPITCH + (32 + 16 * j + 8 * hi) * 2); o[db] = MFMA32(vf, pw, o[db]); } }
; }
; __device__ __forceinline__ float max16(const f32x16& a, const f32x16& b) {
;     float m = fmaxf(a[0], b[0]);
; #pragma unroll
;     for (int r = 1; r < 16; ++r) m = fmaxf(m, fmaxf(a[r], b[r]));
;     return m;
; }
; __device__ __forceinline__ void softmax_pv(f32x16& s0, f32x16& s1, float& mrun, float& lsum, f32x16 (&o)[2], const LAS unsigned char* Vt, int r32, int hi) {
;     float mt = max16(s0, s1); mt = fmaxf(mt, __shfl_xor(mt, 32));
;     const float mnew = fmaxf(mrun, mt), msafe = (mnew == -INFINITY) ? 0.f : mnew;
;     const float alpha = __builtin_amdgcn_exp2f(mrun - msafe);
;     typedef float f32x2v __attribute__((ext_vector_type(2)));
;     const f32x2v mm = {msafe, msafe}; f32x2v ps2 = {0.f, 0.f};
; #pragma unroll
;     for (int r = 0; r < 16; r += 2) {
;         f32x2v d0 = (f32x2v){s0[r], s0[r + 1]} - mm, d1 = (f32x2v){s1[r], s1[r + 1]} - mm;
;         s0[r] = __builtin_amdgcn_exp2f(d0[0]); s0[r + 1] = __builtin_amdgcn_exp2f(d0[1]); s1[r] = __builtin_amdgcn_exp2f(d1[0]); s1[r + 1] = __builtin_amdgcn_exp2f(d1[1]);
;         ps2 += (f32x2v){s0[r], s0[r + 1]}; ps2 += (f32x2v){s1[r], s1[r + 1]}; }
;     lsum = lsum * alpha + (ps2[0] + ps2[1]); mrun = mnew;
; #pragma unroll
;     for (int r = 0; r < 16; ++r) { o[0][r] *= alpha; o[1][r] *= alpha; }
;     pv_tile(o, Vt, s0, s1, r32, hi);
; }
.LBB0_850:
	v_max3_f32 v1, v119, v69, v86
	v_max3_f32 v70, v114, v84, v115
	v_max3_f32 v1, v1, v72, v87
	v_max3_f32 v70, v70, v85, v94
	v_max3_f32 v1, v1, v73, v68
	v_max3_f32 v70, v70, v88, v95
	v_max3_f32 v1, v1, v118, v116
	v_max3_f32 v70, v70, v89, v96
	v_max3_f32 v1, v1, v76, v117
	v_max3_f32 v70, v70, v92, v97
	v_max3_f32 v1, v1, v77, v90
	v_max3_f32 v70, v70, v93, v98
	v_max3_f32 v1, v1, v80, v91
	v_max3_f32 v70, v70, v112, v99
	v_max3_f32 v1, v1, v81, v113
	v_max_f32_e32 v1, v1, v70
	ds_bpermute_b32 v70, v238, v1
	s_waitcnt lgkmcnt(0)
	v_max3_f32 v120, v170, v1, v70
	v_cmp_neq_f32_e32 vcc, s96, v120
	s_nop 1
	v_cndmask_b32_e32 v122, 0, v120, vcc
	v_sub_f32_e32 v1, v170, v122
	v_pk_add_f32 v[68:69], v[68:69], v[122:123] op_sel_hi:[1,0] neg_lo:[0,1] neg_hi:[0,1]
	v_pk_add_f32 v[72:73], v[72:73], v[122:123] op_sel_hi:[1,0] neg_lo:[0,1] neg_hi:[0,1]
	v_pk_add_f32 v[76:77], v[76:77], v[122:123] op_sel_hi:[1,0] neg_lo:[0,1] neg_hi:[0,1]
	v_pk_add_f32 v[80:81], v[80:81], v[122:123] op_sel_hi:[1,0] neg_lo:[0,1] neg_hi:[0,1]
	v_exp_f32_e32 v68, v68
	v_exp_f32_e32 v69, v69
	v_exp_f32_e32 v72, v72
	v_exp_f32_e32 v73, v73
	v_exp_f32_e32 v76, v76
	v_exp_f32_e32 v77, v77
	v_pk_add_f32 v[82:83], v[90:91], v[122:123] op_sel_hi:[1,0] neg_lo:[0,1] neg_hi:[0,1]
	v_exp_f32_e32 v80, v80
	v_exp_f32_e32 v81, v81
	v_pk_add_f32 v[90:91], v[94:95], v[122:123] op_sel_hi:[1,0] neg_lo:[0,1] neg_hi:[0,1]
	v_pk_add_f32 v[94:95], v[96:97], v[122:123] op_sel_hi:[1,0] neg_lo:[0,1] neg_hi:[0,1]
	v_pk_add_f32 v[96:97], v[112:113], v[122:123] op_sel_hi:[1,0] neg_lo:[0,1] neg_hi:[0,1]
	v_exp_f32_e32 v112, v1
	v_add3_u32 v1, s13, v124, v237
	v_pk_add_f32 v[70:71], v[118:119], v[122:123] op_sel_hi:[1,0] neg_lo:[0,1] neg_hi:[0,1]
	v_pk_add_f32 v[74:75], v[86:87], v[122:123] op_sel_hi:[1,0] neg_lo:[0,1] neg_hi:[0,1]
	v_pk_add_f32 v[78:79], v[116:117], v[122:123] op_sel_hi:[1,0] neg_lo:[0,1] neg_hi:[0,1]
	v_pk_add_f32 v[84:85], v[84:85], v[122:123] op_sel_hi:[1,0] neg_lo:[0,1] neg_hi:[0,1]
	v_pk_add_f32 v[86:87], v[114:115], v[122:123] op_sel_hi:[1,0] neg_lo:[0,1] neg_hi:[0,1]
	v_pk_add_f32 v[88:89], v[88:89], v[122:123] op_sel_hi:[1,0] neg_lo:[0,1] neg_hi:[0,1]
	v_pk_add_f32 v[92:93], v[92:93], v[122:123] op_sel_hi:[1,0] neg_lo:[0,1] neg_hi:[0,1]
	v_pk_add_f32 v[98:99], v[98:99], v[122:123] op_sel_hi:[1,0] neg_lo:[0,1] neg_hi:[0,1]
	ds_read_b128 v[122:125], v1 offset:9216
	ds_read_b128 v[126:129], v1 offset:9248
	v_pk_mul_f32 v[66:67], v[66:67], v[112:113] op_sel_hi:[1,0]
	v_pk_mul_f32 v[64:65], v[64:65], v[112:113] op_sel_hi:[1,0]
	v_pk_mul_f32 v[62:63], v[62:63], v[112:113] op_sel_hi:[1,0]
	v_pk_mul_f32 v[60:61], v[60:61], v[112:113] op_sel_hi:[1,0]
	v_pk_mul_f32 v[58:59], v[58:59], v[112:113] op_sel_hi:[1,0]
	v_pk_mul_f32 v[56:57], v[56:57], v[112:113] op_sel_hi:[1,0]
	v_pk_mul_f32 v[54:55], v[54:55], v[112:113] op_sel_hi:[1,0]
	v_pk_mul_f32 v[52:53], v[52:53], v[112:113] op_sel_hi:[1,0]
	v_cvt_pk_bf16_f32 v114, v68, v69
	v_cvt_pk_bf16_f32 v115, v72, v73
	v_cvt_pk_bf16_f32 v116, v76, v77
	v_cvt_pk_bf16_f32 v117, v80, v81
	v_pk_mul_f32 v[50:51], v[50:51], v[112:113] op_sel_hi:[1,0]
	v_pk_mul_f32 v[48:49], v[48:49], v[112:113] op_sel_hi:[1,0]
	s_waitcnt lgkmcnt(1)
	v_mfma_f32_32x32x16_bf16 v[52:67], v[122:125], v[114:117], v[52:67]
	ds_read_b128 v[122:125], v1 offset:13824
	v_mul_f32_e64 v46, v46, v112
	v_mul_f32_e64 v47, v47, v112
	v_mul_f32_e64 v44, v44, v112
	v_mul_f32_e64 v45, v45, v112
	v_pk_mul_f32 v[42:43], v[42:43], v[112:113] op_sel_hi:[1,0]
	v_pk_mul_f32 v[40:41], v[40:41], v[112:113] op_sel_hi:[1,0]
	v_pk_mul_f32 v[38:39], v[38:39], v[112:113] op_sel_hi:[1,0]
	v_pk_mul_f32 v[36:37], v[36:37], v[112:113] op_sel_hi:[1,0]
	v_exp_f32_e32 v84, v84
	v_exp_f32_e32 v85, v85
	s_waitcnt lgkmcnt(0)
	v_mfma_f32_32x32x16_bf16 v[36:51], v[122:125], v[114:117], v[36:51]
	ds_read_b128 v[122:125], v1 offset:13856
	v_exp_f32_e32 v88, v88
	v_exp_f32_e32 v89, v89
	v_exp_f32_e32 v92, v92
	v_exp_f32_e32 v93, v93
	v_exp_f32_e32 v96, v96
	v_exp_f32_e32 v97, v97
	v_cvt_pk_bf16_f32 v114, v84, v85
	v_cvt_pk_bf16_f32 v115, v88, v89
	v_cvt_pk_bf16_f32 v116, v92, v93
	v_cvt_pk_bf16_f32 v117, v96, v97
	v_exp_f32_e32 v70, v70
	v_exp_f32_e32 v71, v71
	s_waitcnt lgkmcnt(0)
	v_mfma_f32_32x32x16_bf16 v[36:51], v[122:125], v[114:117], v[36:51]
	ds_read_b128 v[122:125], v1 offset:9280
	v_exp_f32_e32 v74, v74
	v_exp_f32_e32 v75, v75
	v_exp_f32_e32 v78, v78
	v_exp_f32_e32 v79, v79
	v_exp_f32_e32 v82, v82
	v_exp_f32_e32 v83, v83
	v_mfma_f32_32x32x16_bf16 v[52:67], v[126:129], v[114:117], v[52:67]
	v_cvt_pk_bf16_f32 v114, v70, v71
	v_cvt_pk_bf16_f32 v115, v74, v75
	v_cvt_pk_bf16_f32 v116, v78, v79
	v_cvt_pk_bf16_f32 v117, v82, v83
	v_exp_f32_e32 v86, v86
	v_exp_f32_e32 v87, v87
	v_exp_f32_e32 v90, v90
	s_waitcnt lgkmcnt(0)
	v_mfma_f32_32x32x16_bf16 v[52:67], v[122:125], v[114:117], v[52:67]
	ds_read_b128 v[122:125], v1 offset:13888
	v_exp_f32_e32 v91, v91
	v_exp_f32_e32 v94, v94
	v_exp_f32_e32 v95, v95
	v_exp_f32_e32 v98, v98
	v_exp_f32_e32 v99, v99
	s_andn2_b64 vcc, exec, s[10:11]
	s_waitcnt lgkmcnt(0)
	v_mfma_f32_32x32x16_bf16 v[36:51], v[122:125], v[114:117], v[36:51]
	ds_read_b128 v[122:125], v1 offset:9312
	v_cvt_pk_bf16_f32 v114, v86, v87
	v_cvt_pk_bf16_f32 v115, v90, v91
	v_cvt_pk_bf16_f32 v116, v94, v95
	v_cvt_pk_bf16_f32 v117, v98, v99
	s_waitcnt lgkmcnt(0)
	s_nop 0
	v_mfma_f32_32x32x16_bf16 v[52:67], v[122:125], v[114:117], v[52:67]
	ds_read_b128 v[122:125], v1 offset:13920
	s_waitcnt lgkmcnt(0)
	v_mfma_f32_32x32x16_bf16 v[36:51], v[122:125], v[114:117], v[36:51]
	s_cbranch_vccnz .LBB0_852
	s_lshl_b32 s4, s12, 1
	s_xor_b32 s4, s4, 2
	s_mulk_i32 s4, 0x2400
	v_add_u32_e32 v1, s4, v157
	s_waitcnt vmcnt(1)
	ds_write_b128 v1, v[100:103]
	s_waitcnt vmcnt(0)
	ds_write_b128 v1, v[104:107] offset:9216

; #define LAS __attribute__((address_space(3)))
; #define MFMA32(a, b, c) __builtin_amdgcn_mfma_f32_32x32x16_bf16((a), (b), (c), 0, 0, 0)
; __device__ __forceinline__ int crow(int r, int hi) { return (r & 3) + 8 * (r >> 2) + 4 * hi; }
; __device__ __forceinline__ void qk_tile(f32x16& s0, f32x16& s1, const LAS unsigned char* Kt, const bf16x8 (&qf)[4], int r32, int hi) {
; #pragma unroll
;     for (int d0 = 0; d0 < 4; ++d0) {
;         const bf16x8 k0 = *(const LAS bf16x8*)(Kt + r32 * TPITCH + (16 * d0 + 8 * hi) * 2);
;         const bf16x8 k1 = *(const LAS bf16x8*)(Kt + (r32 + 32) * TPITCH + (16 * d0 + 8 * hi) * 2);
;         s0 = MFMA32(k0, qf[d0], s0); s1 = MFMA32(k1, qf[d0], s1);
;     }
; }
; template <int MODE> ...
;     ...
;         f32x16 s0, s1; const int dj = qb - j;
;         const bool sel = (MODE == 0) ? (((selmask >> j) & 1u) != 0u) : true;
;         if (dj >= 3) {
;             const float bi = sel ? b31 : -INFINITY;
; #pragma unroll
;             for (int r = 0; r < 16; ++r) { s0[r] = bi; s1[r] = bi; }
;         } else {
;             const int e0 = 64 * dj + iq + 64;
; #pragma unroll
;             for (int r = 0; r < 16; ++r) { const int kl = crow(r, hi); s0[r] = biasW[e0 - kl]; s1[r] = biasW[e0 - kl - 32]; }
;         }
;         qk_tile(s0, s1, Kt, qf, r32, hi);
.LBB0_859:
	s_cmp_lg_u32 s13, s17
	s_cbranch_scc0 .Lwin_edge
	s_add_i32 s10, s17, -8
	s_and_b32 s10, s10, 1
	s_mul_i32 s11, s10, 0x4800
	v_lshlrev_b32_e32 v188, 4, v248
	v_mov_b32_e32 v102, v100
	v_mov_b32_e32 v103, v100
	v_add3_u32 v189, s11, v237, v188
	ds_read_b128 v[190:193], v189
	ds_read_b128 v[194:197], v189 offset:4608
	ds_read_b128 v[198:201], v189 offset:32
	ds_read_b128 v[202:205], v189 offset:4640
	v_mov_b64_e32 v[118:119], v[102:103]
	v_mov_b64_e32 v[120:121], v[102:103]
	v_mov_b64_e32 v[122:123], v[102:103]
	v_mov_b64_e32 v[124:125], v[102:103]
	v_mov_b64_e32 v[126:127], v[102:103]
	v_mov_b64_e32 v[128:129], v[102:103]
	v_mov_b64_e32 v[130:131], v[102:103]
	v_mov_b64_e32 v[132:133], v[102:103]
	v_mov_b64_e32 v[104:105], v[102:103]
	v_mov_b64_e32 v[106:107], v[102:103]
	v_mov_b64_e32 v[108:109], v[102:103]
	v_mov_b64_e32 v[110:111], v[102:103]
	v_mov_b64_e32 v[112:113], v[102:103]
	v_mov_b64_e32 v[114:115], v[102:103]
	v_mov_b64_e32 v[116:117], v[102:103]
	s_waitcnt lgkmcnt(3)
	v_mfma_f32_32x32x16_bf16 v[118:133], v[190:193], v[142:145], v[118:133]
	ds_read_b128 v[190:193], v189 offset:64
	s_waitcnt lgkmcnt(3)
	v_mfma_f32_32x32x16_bf16 v[102:117], v[194:197], v[142:145], v[102:117]
	ds_read_b128 v[194:197], v189 offset:4672
	s_waitcnt lgkmcnt(3)
	v_mfma_f32_32x32x16_bf16 v[118:133], v[198:201], v[134:137], v[118:133]
	ds_read_b128 v[198:201], v189 offset:96
	s_waitcnt lgkmcnt(3)
	v_mfma_f32_32x32x16_bf16 v[102:117], v[202:205], v[134:137], v[102:117]
	ds_read_b128 v[202:205], v189 offset:4704
	s_waitcnt lgkmcnt(3)
	v_mfma_f32_32x32x16_bf16 v[118:133], v[190:193], v[138:141], v[118:133]
	s_waitcnt lgkmcnt(2)
	v_mfma_f32_32x32x16_bf16 v[102:117], v[194:197], v[138:141], v[102:117]
	s_waitcnt lgkmcnt(1)
	v_mfma_f32_32x32x16_bf16 v[118:133], v[198:201], v[146:149], v[118:133]
	s_waitcnt lgkmcnt(0)
	v_mfma_f32_32x32x16_bf16 v[102:117], v[202:205], v[146:149], v[102:117]
	s_nop 6
	s_branch .LBB0_865

; #define LAS __attribute__((address_space(3)))
; #define MFMA32(a, b, c) __builtin_amdgcn_mfma_f32_32x32x16_bf16((a), (b), (c), 0, 0, 0)
; __device__ __forceinline__ void pv_tile(f32x16 (&o)[2], const LAS unsigned char* Vt, const f32x16& p0, const f32x16& p1, int r32, int hi) {
; #pragma unroll
;     for (int j = 0; j < 2; ++j) { const bf16x8 pw = pack8(p0, j);
; #pragma unroll
;         for (int db = 0; db < 2; ++db) { const bf16x8 vf = *(const LAS bf16x8*)(Vt + (r32 + 32 * db) * TPITCH + (16 * j + 8 * hi) * 2); o[db] = MFMA32(vf, pw, o[db]); } }
; #pragma unroll
;     for (int j = 0; j < 2; ++j) { const bf16x8 pw = pack8(p1, j);
; #pragma unroll
;         for (int db = 0; db < 2; ++db) { const bf16x8 vf = *(const LAS bf16x8*)(Vt + (r32 + 32 * db) * TPITCH + (32 + 16 * j + 8 * hi) * 2); o[db] = MFMA32(vf, pw, o[db]); } }
; }
; __device__ __forceinline__ float max16(const f32x16& a, const f32x16& b) {
;     float m = fmaxf(a[0], b[0]);
; #pragma unroll
;     for (int r = 1; r < 16; ++r) m = fmaxf(m, fmaxf(a[r], b[r]));
;     return m;
; }
; __device__ __forceinline__ void softmax_pv(f32x16& s0, f32x16& s1, float& mrun, float& lsum, f32x16 (&o)[2], const LAS unsigned char* Vt, int r32, int hi) {
;     float mt = max16(s0, s1); mt = fmaxf(mt, __shfl_xor(mt, 32));
;     const float mnew = fmaxf(mrun, mt), msafe = (mnew == -INFINITY) ? 0.f : mnew;
;     const float alpha = __builtin_amdgcn_exp2f(mrun - msafe);
;     typedef float f32x2v __attribute__((ext_vector_type(2)));
;     const f32x2v mm = {msafe, msafe}; f32x2v ps2 = {0.f, 0.f};
; #pragma unroll
;     for (int r = 0; r < 16; r += 2) {
;         f32x2v d0 = (f32x2v){s0[r], s0[r + 1]} - mm, d1 = (f32x2v){s1[r], s1[r + 1]} - mm;
;         s0[r] = __builtin_amdgcn_exp2f(d0[0]); s0[r + 1] = __builtin_amdgcn_exp2f(d0[1]); s1[r] = __builtin_amdgcn_exp2f(d1[0]); s1[r + 1] = __builtin_amdgcn_exp2f(d1[1]);
;         ps2 += (f32x2v){s0[r], s0[r + 1]}; ps2 += (f32x2v){s1[r], s1[r + 1]}; }
;     lsum = lsum * alpha + (ps2[0] + ps2[1]); mrun = mnew;
; #pragma unroll
;     for (int r = 0; r < 16; ++r) { o[0][r] *= alpha; o[1][r] *= alpha; }
;     pv_tile(o, Vt, s0, s1, r32, hi);
; }
.LBB0_865:
	s_nop 4
	v_max3_f32 v172, v103, v119, v104
	v_max3_f32 v173, v110, v126, v111
	v_max3_f32 v172, v172, v120, v105
	v_max3_f32 v173, v173, v127, v112
	v_max3_f32 v172, v172, v121, v118
	v_max3_f32 v173, v173, v128, v113
	v_max3_f32 v172, v172, v102, v106
	v_max3_f32 v173, v173, v129, v114
	v_max3_f32 v172, v172, v122, v107
	v_max3_f32 v173, v173, v130, v115
	v_max3_f32 v172, v172, v123, v108
	v_max3_f32 v173, v173, v131, v116
	v_max3_f32 v172, v172, v124, v109
	v_max3_f32 v173, v173, v132, v117
	v_max3_f32 v172, v172, v125, v133
	v_max_f32_e32 v172, v172, v173
	ds_bpermute_b32 v173, v238, v172
	s_waitcnt lgkmcnt(0)
	v_max3_f32 v173, v245, v172, v173
	v_cmp_neq_f32_e32 vcc, s96, v173
	s_nop 1
	v_cndmask_b32_e32 v172, 0, v173, vcc
	v_pk_add_f32 v[118:119], v[118:119], v[172:173] op_sel_hi:[1,0] neg_lo:[0,1] neg_hi:[0,1]
	v_pk_add_f32 v[186:187], v[102:103], v[172:173] op_sel_hi:[1,0] neg_lo:[0,1] neg_hi:[0,1]
	v_sub_f32_e32 v189, v245, v172
	v_exp_f32_e32 v102, v118
	v_exp_f32_e32 v103, v119
	v_exp_f32_e32 v118, v186
	v_exp_f32_e32 v119, v187
	v_pk_add_f32 v[120:121], v[120:121], v[172:173] op_sel_hi:[1,0] neg_lo:[0,1] neg_hi:[0,1]
	v_pk_add_f32 v[186:187], v[104:105], v[172:173] op_sel_hi:[1,0] neg_lo:[0,1] neg_hi:[0,1]
	v_pk_add_f32 v[122:123], v[122:123], v[172:173] op_sel_hi:[1,0] neg_lo:[0,1] neg_hi:[0,1]
	v_exp_f32_e32 v104, v120
	v_exp_f32_e32 v105, v121
	v_exp_f32_e32 v120, v186
	v_exp_f32_e32 v121, v187
	v_pk_add_f32 v[186:187], v[106:107], v[172:173] op_sel_hi:[1,0] neg_lo:[0,1] neg_hi:[0,1]
	v_exp_f32_e32 v106, v122
	v_exp_f32_e32 v107, v123
	v_pk_add_f32 v[122:123], v[124:125], v[172:173] op_sel_hi:[1,0] neg_lo:[0,1] neg_hi:[0,1]
	v_pk_add_f32 v[124:125], v[126:127], v[172:173] op_sel_hi:[1,0] neg_lo:[0,1] neg_hi:[0,1]
	v_pk_add_f32 v[126:127], v[128:129], v[172:173] op_sel_hi:[1,0] neg_lo:[0,1] neg_hi:[0,1]
	v_exp_f32_e32 v128, v189
	v_exp_f32_e32 v122, v122
	v_exp_f32_e32 v123, v123
	v_cvt_pk_bf16_f32 v192, v102, v103
	v_pk_mul_f32 v[82:83], v[82:83], v[128:129] op_sel_hi:[1,0]
	v_pk_mul_f32 v[80:81], v[80:81], v[128:129] op_sel_hi:[1,0]
	v_pk_mul_f32 v[78:79], v[78:79], v[128:129] op_sel_hi:[1,0]
	v_pk_mul_f32 v[76:77], v[76:77], v[128:129] op_sel_hi:[1,0]
	v_pk_mul_f32 v[74:75], v[74:75], v[128:129] op_sel_hi:[1,0]
	v_pk_mul_f32 v[72:73], v[72:73], v[128:129] op_sel_hi:[1,0]
	v_pk_mul_f32 v[70:71], v[70:71], v[128:129] op_sel_hi:[1,0]
	v_add3_u32 v129, s11, v188, v237
	ds_read_b128 v[188:191], v129 offset:9216
	ds_read_b128 v[196:199], v129 offset:13824
	v_pk_mul_f32 v[68:69], v[68:69], v[128:129] op_sel_hi:[1,0]
	v_cvt_pk_bf16_f32 v193, v104, v105
	v_cvt_pk_bf16_f32 v194, v106, v107
	v_cvt_pk_bf16_f32 v195, v122, v123
	v_pk_add_f32 v[130:131], v[130:131], v[172:173] op_sel_hi:[1,0] neg_lo:[0,1] neg_hi:[0,1]
	v_pk_add_f32 v[132:133], v[132:133], v[172:173] op_sel_hi:[1,0] neg_lo:[0,1] neg_hi:[0,1]
	s_waitcnt lgkmcnt(1)
	v_mfma_f32_32x32x16_bf16 v[68:83], v[188:191], v[192:195], v[68:83]
	ds_read_b128 v[188:191], v129 offset:9248
	v_exp_f32_e32 v124, v124
	v_exp_f32_e32 v125, v125
	v_exp_f32_e32 v126, v126
	v_exp_f32_e32 v127, v127
	v_exp_f32_e32 v130, v130
	v_exp_f32_e32 v131, v131
	v_exp_f32_e32 v132, v132
	v_exp_f32_e32 v133, v133
	v_pk_mul_f32 v[98:99], v[98:99], v[128:129] op_sel_hi:[1,0]
	v_pk_mul_f32 v[96:97], v[96:97], v[128:129] op_sel_hi:[1,0]
	v_pk_mul_f32 v[94:95], v[94:95], v[128:129] op_sel_hi:[1,0]
	v_pk_mul_f32 v[92:93], v[92:93], v[128:129] op_sel_hi:[1,0]
	v_pk_mul_f32 v[90:91], v[90:91], v[128:129] op_sel_hi:[1,0]
	v_pk_mul_f32 v[88:89], v[88:89], v[128:129] op_sel_hi:[1,0]
	v_pk_mul_f32 v[86:87], v[86:87], v[128:129] op_sel_hi:[1,0]
	v_pk_mul_f32 v[84:85], v[84:85], v[128:129] op_sel_hi:[1,0]
	v_pk_add_f32 v[108:109], v[108:109], v[172:173] op_sel_hi:[1,0] neg_lo:[0,1] neg_hi:[0,1]
	v_exp_f32_e32 v186, v186
	s_waitcnt lgkmcnt(1)
	v_mfma_f32_32x32x16_bf16 v[84:99], v[196:199], v[192:195], v[84:99]
	v_cvt_pk_bf16_f32 v192, v124, v125
	v_cvt_pk_bf16_f32 v193, v126, v127
	v_cvt_pk_bf16_f32 v194, v130, v131
	v_cvt_pk_bf16_f32 v195, v132, v133
	ds_read_b128 v[196:199], v129 offset:13856
	v_exp_f32_e32 v187, v187
	v_exp_f32_e32 v108, v108
	s_waitcnt lgkmcnt(1)
	v_mfma_f32_32x32x16_bf16 v[68:83], v[188:191], v[192:195], v[68:83]
	ds_read_b128 v[188:191], v129 offset:9280
	v_exp_f32_e32 v109, v109
	v_pk_add_f32 v[110:111], v[110:111], v[172:173] op_sel_hi:[1,0] neg_lo:[0,1] neg_hi:[0,1]
	v_pk_add_f32 v[112:113], v[112:113], v[172:173] op_sel_hi:[1,0] neg_lo:[0,1] neg_hi:[0,1]
	v_pk_add_f32 v[114:115], v[114:115], v[172:173] op_sel_hi:[1,0] neg_lo:[0,1] neg_hi:[0,1]
	v_pk_add_f32 v[116:117], v[116:117], v[172:173] op_sel_hi:[1,0] neg_lo:[0,1] neg_hi:[0,1]
	v_exp_f32_e32 v110, v110
	s_waitcnt lgkmcnt(1)
	v_mfma_f32_32x32x16_bf16 v[84:99], v[196:199], v[192:195], v[84:99]
	v_cvt_pk_bf16_f32 v192, v118, v119
	v_cvt_pk_bf16_f32 v193, v120, v121
	v_cvt_pk_bf16_f32 v194, v186, v187
	v_cvt_pk_bf16_f32 v195, v108, v109
	ds_read_b128 v[196:199], v129 offset:13888
	v_exp_f32_e32 v111, v111
	v_exp_f32_e32 v112, v112
	s_waitcnt lgkmcnt(1)
	v_mfma_f32_32x32x16_bf16 v[68:83], v[188:191], v[192:195], v[68:83]
	ds_read_b128 v[188:191], v129 offset:9312
	v_exp_f32_e32 v113, v113
	v_exp_f32_e32 v114, v114
	v_exp_f32_e32 v115, v115
	v_exp_f32_e32 v116, v116
	v_exp_f32_e32 v117, v117
	s_andn2_b64 vcc, exec, s[4:5]
	s_waitcnt lgkmcnt(1)
	v_mfma_f32_32x32x16_bf16 v[84:99], v[196:199], v[192:195], v[84:99]
	v_cvt_pk_bf16_f32 v192, v110, v111
	v_cvt_pk_bf16_f32 v193, v112, v113
	v_cvt_pk_bf16_f32 v194, v114, v115
	v_cvt_pk_bf16_f32 v195, v116, v117
	s_waitcnt lgkmcnt(0)
	s_nop 0
	v_mfma_f32_32x32x16_bf16 v[68:83], v[188:191], v[192:195], v[68:83]
	ds_read_b128 v[188:191], v129 offset:13920
	s_waitcnt lgkmcnt(0)
	v_mfma_f32_32x32x16_bf16 v[84:99], v[188:191], v[192:195], v[84:99]
	s_cbranch_vccnz .LBB0_867
	s_lshl_b32 s4, s10, 1
	s_xor_b32 s4, s4, 2
	s_mulk_i32 s4, 0x2400
	v_add_u32_e32 v129, s4, v243
	s_waitcnt vmcnt(1)
	ds_write_b128 v129, v[150:153]
	s_waitcnt vmcnt(0)
	ds_write_b128 v129, v[154:157] offset:9216
